# v7 + static s_setprio 1 for waves 4-7 in the attention phases (AB attention, stick-breaking + MLA)
# baseline (speedup 1.0000x reference)
; #define LAS __attribute__((address_space(3)))
; __device__ __forceinline__ void ab_phase(const h16* H, const float* sinks, h16* Y, h16* PO16, float* LSE, LAS unsigned char* lds, int G) {
;     constexpr int SLOT = 9216, VP = 144, NU = 2560;
;     int tid = threadIdx.x; asm volatile("" : "+v"(tid));
;     const int lane = tid & 63, w = __builtin_amdgcn_readfirstlane(tid >> 6), r32 = lane & 31, hi = lane >> 5;
;     const int isV = tid >> 8, lrow = (tid & 255) >> 3, lcc = tid & 7;
;     const int q4 = (lane & 15) >> 2, p4 = lane & 3, dblk = (lane >> 4) & 1;
;     const int vrd_off = (4 * hi + q4) * VP + dblk * 32 + p4 * 8;
;     LAS unsigned char* wdst = lds + (isV ? 0 : 32 * VP) + lrow * VP + lcc * 16;
;     u32x4 tr[12]; h8 qn[4];
;     ...
;     int U = ((gridDim.x % 8 == 0) ? (int)((blockIdx.x % 8) * (gridDim.x / 8) + blockIdx.x / 8) : (int)blockIdx.x);
.LBB0_205:
	s_or_b64 exec, exec, s[0:1]
	s_and_b32 s0, s84, 7
	s_cmp_eq_u32 s0, 0
	s_mov_b64 s[8:9], s[78:79]
	s_mov_b64 s[44:45], s[76:77]
	s_waitcnt lgkmcnt(0)
	v_mov_b32_e32 v0, v204
	s_setprio 0
	v_mov_b32_e32 v5, v204
	s_cselect_b64 s[4:5], -1, 0
	s_barrier
	v_readfirstlane_b32 s98, v204
	s_lshr_b32 s98, s98, 8
	s_cmp_lg_u32 s98, 0
	s_cbranch_scc0 .Laprio_skip_p2
	s_setprio 1
.Laprio_skip_p2:
	v_writelane_b32 v234, s4, 6
	v_readfirstlane_b32 s13, v5
	s_cmp_lg_u32 s0, 0
	s_mov_b32 s12, s33
	v_writelane_b32 v234, s5, 7
	s_cbranch_scc1 .LBB0_207
	s_and_b32 s0, s2, 7
	s_lshr_b32 s1, s84, 3
	s_mul_i32 s0, s1, s0
	s_lshr_b32 s1, s2, 3
	s_add_i32 s12, s0, s1

; #define WS_SETUP unsigned char* ws = P.ws; asm volatile("" : "+s"(ws)); float* R = P.out; asm volatile("" : "+s"(R)); (void)R;
; __global__ void __launch_bounds__(NWAVES * 64, 2) mega_fwd(Params P) {
;     ...
;     { WS_SETUP TID_SETUP
;             const float* gq = P.in[5]; const float* gkv = P.in[6];
;             for (int row = gw; row < MTOK; row += NGW) {
;                 const h16* hp = H2 + (size_t)row * ODD_INP;
;                 const h8 cq = *(const h8*)(hp + 3072 + 8 * lane); const h4 ck = *(const h4*)(hp + 3584 + 4 * lane);
;                 float xq[8], xk[4], sq = 0.f, sk = 0.f;
; #pragma unroll
;                 for (int e = 0; e < 8; ++e) { xq[e] = (float)cq[e]; sq += xq[e] * xq[e]; }
; #pragma unroll
;                 for (int e = 0; e < 4; ++e) { xk[e] = (float)ck[e]; sk += xk[e] * xk[e]; }
;                 const float rq = 1.f / sqrtf(wave_sum(sq) * (1.f / 512.f) + RMS_EPS), rk = 1.f / sqrtf(wave_sum(sk) * (1.f / 256.f) + RMS_EPS);
.LBB0_806:
	s_or_b64 exec, exec, s[0:1]
	s_mov_b64 s[10:11], s[78:79]
	s_mov_b64 s[0:1], s[76:77]
	s_waitcnt lgkmcnt(0)
	s_barrier
	v_mov_b32_e32 v0, v204
	s_setprio 0
	v_readfirstlane_b32 s98, v204
	s_lshr_b32 s98, s98, 8
	s_cmp_lg_u32 s98, 0
	s_cbranch_scc0 .Laprio_skip_0
	s_setprio 1
.Laprio_skip_0:
	s_nop 0
	v_readfirstlane_b32 s0, v0
	s_ashr_i32 s0, s0, 6
	s_add_i32 s12, s0, s95
	s_cmpk_gt_i32 s12, 0x3fff
	s_cbranch_scc1 .LBB0_811
	v_and_b32_e32 v18, 63, v0
	v_xor_b32_e32 v0, 1, v205
	v_cmp_lt_i32_e32 vcc, v0, v207
	s_add_u32 s14, s10, 0x100000
	v_mov_b32_e32 v1, 0
	v_cndmask_b32_e32 v0, v205, v0, vcc
	v_lshlrev_b32_e32 v19, 2, v0
	v_xor_b32_e32 v0, 2, v205
	v_cmp_lt_i32_e32 vcc, v0, v207
	s_addc_u32 s15, s11, 0
	s_ashr_i32 s13, s12, 31
	v_cndmask_b32_e32 v0, v205, v0, vcc
	v_lshlrev_b32_e32 v20, 2, v0
	v_xor_b32_e32 v0, 4, v205
	v_cmp_lt_i32_e32 vcc, v0, v207
	s_lshl_b64 s[8:9], s[12:13], 6
	v_lshlrev_b32_e32 v12, 1, v18
	v_cndmask_b32_e32 v0, v205, v0, vcc
	v_lshlrev_b32_e32 v21, 2, v0
	v_xor_b32_e32 v0, 8, v205
	v_cmp_lt_i32_e32 vcc, v0, v207
	v_mov_b32_e32 v13, v1
	v_lshlrev_b32_e32 v14, 3, v18
	v_cndmask_b32_e32 v0, v205, v0, vcc
	v_lshlrev_b32_e32 v22, 2, v0
	v_xor_b32_e32 v0, 16, v205
	v_cmp_lt_i32_e32 vcc, v0, v207
	v_lshl_add_u64 v[6:7], s[8:9], 0, v[12:13]
	s_lshl_b64 s[8:9], s[12:13], 9
	v_cndmask_b32_e32 v0, v205, v0, vcc
	v_cmp_lt_i32_e32 vcc, v206, v207
	v_lshlrev_b32_e32 v23, 2, v0
	v_or_b32_e32 v8, s8, v14
	v_cndmask_b32_e32 v0, v205, v206, vcc
	v_lshlrev_b32_e32 v24, 2, v0
	v_lshlrev_b32_e32 v0, 5, v18
	v_mov_b32_e32 v9, s9
	s_mov_b64 s[8:9], 0x18a00000
	v_lshl_add_u64 v[2:3], s[70:71], 0, v[0:1]
	v_lshlrev_b32_e32 v0, 4, v18
	v_lshl_add_u64 v[8:9], v[8:9], 0, s[8:9]
	s_lshl_b64 s[8:9], s[12:13], 10
	v_or_b32_e32 v10, s8, v0
	v_mov_b32_e32 v11, s9
	s_mov_b64 s[8:9], 0x17a00000
	v_lshl_add_u64 v[10:11], v[10:11], 0, s[8:9]
	s_lshl_b64 s[8:9], s[12:13], 13
	s_ashr_i32 s81, s80, 31
	v_or_b32_e32 v12, s8, v12
	v_mov_b32_e32 v13, s9
	v_or_b32_e32 v14, s8, v14
	v_mov_b32_e32 v15, s9
	s_mov_b64 s[24:25], 0xfa01c00
	v_or_b32_e32 v16, s8, v0
	v_mov_b32_e32 v17, s9
	s_mov_b64 s[8:9], 0xfa01800
	s_lshl_b32 s1, s2, 8
	s_lshl_b32 s0, s0, 5
	v_lshl_add_u64 v[4:5], s[72:73], 0, v[0:1]
	v_cmp_gt_u32_e64 s[6:7], 16, v18
	s_lshl_b64 s[16:17], s[80:81], 6
	s_lshl_b64 s[18:19], s[80:81], 9
	s_lshl_b64 s[20:21], s[80:81], 10
	s_lshl_b64 s[22:23], s[80:81], 13
	v_lshl_add_u64 v[14:15], v[14:15], 0, s[24:25]
	v_lshl_add_u64 v[16:17], v[16:17], 0, s[8:9]
	s_add_i32 s3, s1, s0
	s_lshl_b32 s13, s84, 8
	v_mov_b32_e32 v25, 0x358637bd
	s_mov_b32 s24, 0xf800000
	v_mov_b32_e32 v26, 0x260
	s_branch .LBB0_809

; #define LAS __attribute__((address_space(3)))
; #define WS_SETUP unsigned char* ws = P.ws; asm volatile("" : "+s"(ws)); float* R = P.out; asm volatile("" : "+s"(R)); (void)R;
; template <int NC, bool SB>
; __device__ __forceinline__ void attn_task(const AttnArgs& a, LAS unsigned char* vl, int lane, f32x16 (&o)[2], float& lse2) {
;     static_assert(NC == 4, "the per-wave task handles 64-wide heads");
;     constexpr int VP = 144, KP = 144;
;     const int r32 = lane & 31, hi = lane >> 5;
;     h8 qf[4];
;     { const h16* qp = a.q + (long)(a.q0 + r32) * a.qstride + 8 * hi;
; #pragma unroll
;       for (int c = 0; c < 4; ++c) qf[c] = *(const h8*)(qp + 16 * c); }
; #pragma unroll
;     for (int r = 0; r < 16; ++r) { o[0][r] = 0.f; o[1][r] = 0.f; }
;     float m = a.sink2, l = (a.sink2 > -1e30f) ? 1.f : 0.f, carry = 0.f;
;     const int vrow = lane >> 3, vcc = lane & 7;
;     const int q4 = (lane & 15) >> 2, p4 = lane & 3, dblk = (lane >> 4) & 1;
;     LAS unsigned char* vrd = vl + (4 * hi + q4) * VP + dblk * 32 + p4 * 8;
; __global__ void __launch_bounds__(NWAVES * 64, 2) mega_fwd(Params P) {
;     ...
;     { WS_SETUP TID_SETUP
;             for (int T = gw; T < 8192; T += NGW) {
;                 const int b = T >> 10, h = (T >> 6) & 15, qb = T & 63;
;                 AttnArgs a; f32x16 o[2]; float lse2;
;                 a.q0 = qb * 32; a.kt_hi = qb; a.kt_lo = 0; a.rmax = 1 << 30; a.slope2 = 0.f; a.sink2 = -INFINITY;
;                 const h16* base = H2 + (size_t)(b * SEQ) * ODD_INP + h * 64;
;                 a.q = base; a.k = base + 1024; a.v = base + 2048; a.qstride = a.kstride = a.vstride = ODD_INP; a.k2 = nullptr; a.k2stride = 0; a.c1 = 0.125f;
;                 attn_task<4, true>(a, wlds, lane, o, lse2);
.LBB0_955:
	s_or_b64 exec, exec, s[0:1]
	s_mov_b64 s[48:49], s[78:79]
	s_mov_b64 s[0:1], s[76:77]
	s_waitcnt lgkmcnt(0)
	s_barrier
	v_mov_b32_e32 v0, v204
	s_setprio 0
	v_readfirstlane_b32 s98, v204
	s_lshr_b32 s98, s98, 8
	s_cmp_lg_u32 s98, 0
	s_cbranch_scc0 .Laprio_skip_1
	s_setprio 1
.Laprio_skip_1:
	s_nop 0
	v_readfirstlane_b32 s1, v0
	s_ashr_i32 s0, s1, 6
	s_add_i32 s3, s0, s95
	s_cmpk_gt_i32 s3, 0x1fff
	s_cbranch_scc1 .LBB0_967
	s_lshl_b32 s0, s0, 14
	v_bfe_u32 v3, v0, 5, 1
	s_lshr_b32 s1, s1, 6
	s_add_i32 s0, s0, 0
	v_lshrrev_b32_e32 v6, 2, v0
	v_lshlrev_b32_e32 v4, 2, v3
	s_add_u32 s67, s48, 0xfa00000
	v_and_b32_e32 v160, 31, v0
	v_and_or_b32 v6, v6, 3, v4
	v_lshlrev_b32_e32 v7, 1, v0
	v_and_b32_e32 v1, 63, v0
	s_addc_u32 s70, s49, 0
	v_bfe_u32 v161, v0, 3, 3
	v_and_b32_e32 v5, 7, v0
	s_movk_i32 s6, 0x90
	v_mul_u32_u24_e32 v6, 0x90, v6
	v_and_b32_e32 v7, 32, v7
	v_lshlrev_b32_e32 v0, 3, v0
	v_mov_b32_e32 v8, s0
	v_sub_u32_e32 v9, v160, v4
	v_lshlrev_b32_e32 v2, 3, v3
	v_mov_b32_e32 v145, 0
	v_add3_u32 v6, s0, v6, v7
	v_and_b32_e32 v7, 24, v0
	v_lshlrev_b32_e32 v0, 3, v5
	v_lshl_add_u32 v5, v5, 4, s0
	v_mad_u32_u24 v8, v160, s6, v8
	v_lshlrev_b32_e32 v3, 4, v3
	v_cmp_gt_u32_e64 s[6:7], 32, v1
	v_mul_u32_u24_e32 v1, 0x90, v161
	v_cmp_lt_i32_e64 s[8:9], 1, v9
	v_cmp_lt_i32_e64 s[10:11], 0, v9
	v_cmp_lt_i32_e64 s[12:13], 3, v9
	v_cmp_lt_i32_e64 s[14:15], 2, v9
	v_cmp_lt_i32_e64 s[16:17], 9, v9
	v_cmp_lt_i32_e64 s[18:19], 8, v9
	v_cmp_lt_i32_e64 s[20:21], 11, v9
	v_cmp_lt_i32_e64 s[22:23], 10, v9
	v_cmp_lt_i32_e64 s[24:25], 17, v9
	v_cmp_lt_i32_e64 s[26:27], 16, v9
	v_cmp_lt_i32_e64 s[28:29], 19, v9
	v_cmp_lt_i32_e64 s[30:31], 18, v9
	v_cmp_lt_i32_e64 s[34:35], 25, v9
	v_cmp_lt_i32_e64 s[36:37], 24, v9
	v_cmp_lt_i32_e64 s[38:39], 27, v9
	v_cmp_lt_i32_e64 s[40:41], 26, v9
	s_add_u32 s60, s48, 0xba00000
	v_lshlrev_b32_e32 v9, 12, v161
	s_mov_b32 s51, 0
	v_or_b32_e32 v162, 0xffffffa0, v161
	s_addc_u32 s61, s49, 0
	s_add_i32 s71, s95, s1
	s_lshl_b32 s72, s84, 3
	v_lshlrev_b32_e32 v146, 1, v2
	v_mov_b32_e32 v147, v145
	v_lshlrev_b32_e32 v148, 1, v0
	v_mov_b32_e32 v149, v145
	s_mov_b64 s[62:63], 0x800
	s_mov_b64 s[64:65], 0x1000
	v_lshlrev_b32_e32 v163, 1, v9
	s_mov_b32 s66, 0x3e000000
	s_mov_b32 s73, 0xbfb8aa3b
	s_mov_b32 s74, 0x800000
	s_mov_b32 s75, 0x3f317217
	s_mov_b32 s81, 0x7f800000
	s_mov_b32 s82, 0x42200000
	v_lshlrev_b32_e32 v150, 1, v4
	v_add_u32_e32 v164, v5, v1
	v_add_u32_e32 v165, v8, v3
	v_mov_b32_e32 v166, 0x41b17218
	v_mov_b32_e32 v167, 0xff800000
	v_add_u32_e32 v168, v6, v7
	s_branch .LBB0_958

; __device__ __forceinline__ void mla_phase(const h16* Q2, const h16* KV, const h16* KR, h16* Y2, LAS unsigned char* lds, int G) {
;     ...
;     for (int slot = ((gridDim.x % 8 == 0) ? (int)((blockIdx.x % 8) * (gridDim.x / 8) + blockIdx.x / 8) : (int)blockIdx.x); slot < 256; slot += G) {
; __global__ void __launch_bounds__(NWAVES * 64, 2) mega_fwd(Params P) {
;     ...
;             __syncthreads();
;             mla_phase(Q2, KV, KR, Y2, lds, G);
.LBB0_967:
	v_readlane_b32 s0, v234, 6
	v_mov_b32_e32 v0, v204
	s_setprio 0
	v_readfirstlane_b32 s98, v204
	s_lshr_b32 s98, s98, 8
	s_cmp_lg_u32 s98, 0
	s_cbranch_scc0 .Laprio_skip_2
	s_setprio 1
.Laprio_skip_2:
	v_readlane_b32 s1, v234, 7
	s_waitcnt lgkmcnt(0)
	s_barrier
	s_andn2_b64 vcc, exec, s[0:1]
	v_readfirstlane_b32 s0, v0
	s_cbranch_vccz .LBB0_969
	s_cmpk_gt_i32 s33, 0xff
	s_cbranch_scc0 .LBB0_970
	s_branch .LBB0_1004
